# phase 1: all 16 scale/shift loads hoisted above the row math, next iteration row prefetched into spare registers, preamble loads parallelised (phase itself 117us to 43us by in-kernel timing)
# speedup vs baseline: 1.0122x; 1.0004x over previous
; __device__ __forceinline__ unsigned cvt_pk_bf16(float lo, float hi) { unsigned r; asm volatile("v_cvt_pk_bf16_f32 %0, %1, %2" : "=v"(r) : "v"(lo), "v"(hi)); return r; }
; __device__ __forceinline__ void phase_ln_in(const Frame& F) {
;     ...
;     for (int k = F.tid; k < D; k += NTHREADS) { const float* sp = win + (size_t)k * NIN + 9216;
; #pragma unroll
;         for (int q = 0; q < 4; ++q) { const f32x4 v = *(const f32x4*)(sp + 4 * q); const unsigned w01 = cvt_pk_bf16(v[0], v[1]), w23 = cvt_pk_bf16(v[2], v[3]);
;             wgB[(4 * q + 0) * LP + k] = (bf16_t)(w01 & 0xffffu); wgB[(4 * q + 1) * LP + k] = (bf16_t)(w01 >> 16); wgB[(4 * q + 2) * LP + k] = (bf16_t)(w23 & 0xffffu); wgB[(4 * q + 3) * LP + k] = (bf16_t)(w23 >> 16); } }
;     __syncthreads();
.LBB0_145:
	global_load_dwordx4 v[100:103], v[0:1], off
	global_load_dwordx4 v[104:107], v[0:1], off offset:16
	global_load_dwordx4 v[108:111], v[0:1], off offset:32
	global_load_dwordx4 v[112:115], v[0:1], off offset:48
	v_lshl_add_u64 v[0:1], v[0:1], 0, s[6:7]
	global_load_dwordx4 v[116:119], v[0:1], off
	global_load_dwordx4 v[120:123], v[0:1], off offset:16
	global_load_dwordx4 v[124:127], v[0:1], off offset:32
	global_load_dwordx4 v[128:131], v[0:1], off offset:48
	v_lshl_add_u64 v[0:1], v[0:1], 0, s[6:7]
	global_load_dwordx4 v[132:135], v[0:1], off
	global_load_dwordx4 v[136:139], v[0:1], off offset:16
	global_load_dwordx4 v[140:143], v[0:1], off offset:32
	global_load_dwordx4 v[148:151], v[0:1], off offset:48
	v_lshl_add_u64 v[0:1], v[0:1], 0, s[6:7]
	global_load_dwordx4 v[152:155], v[0:1], off
	global_load_dwordx4 v[156:159], v[0:1], off offset:16
	global_load_dwordx4 v[160:163], v[0:1], off offset:32
	global_load_dwordx4 v[164:167], v[0:1], off offset:48
	s_waitcnt vmcnt(15)
	v_cvt_pk_bf16_f32 v8, v100, v101
	v_cvt_pk_bf16_f32 v9, v102, v103
	ds_write_b16 v3, v8 offset:0
	ds_write_b16_d16_hi v3, v8 offset:4128
	ds_write_b16 v3, v9 offset:8256
	ds_write_b16_d16_hi v3, v9 offset:12384
	s_waitcnt vmcnt(14)
	v_cvt_pk_bf16_f32 v8, v104, v105
	v_cvt_pk_bf16_f32 v9, v106, v107
	ds_write_b16 v3, v8 offset:16512
	ds_write_b16_d16_hi v3, v8 offset:20640
	ds_write_b16 v3, v9 offset:24768
	ds_write_b16_d16_hi v3, v9 offset:28896
	s_waitcnt vmcnt(13)
	v_cvt_pk_bf16_f32 v8, v108, v109
	v_cvt_pk_bf16_f32 v9, v110, v111
	ds_write_b16 v3, v8 offset:33024
	ds_write_b16_d16_hi v3, v8 offset:37152
	ds_write_b16 v3, v9 offset:41280
	ds_write_b16_d16_hi v3, v9 offset:45408
	s_waitcnt vmcnt(12)
	v_cvt_pk_bf16_f32 v8, v112, v113
	v_cvt_pk_bf16_f32 v9, v114, v115
	ds_write_b16 v3, v8 offset:49536
	ds_write_b16_d16_hi v3, v8 offset:53664
	ds_write_b16 v3, v9 offset:57792
	ds_write_b16_d16_hi v3, v9 offset:61920
	s_waitcnt vmcnt(11)
	v_cvt_pk_bf16_f32 v8, v116, v117
	v_cvt_pk_bf16_f32 v9, v118, v119
	ds_write_b16 v3, v8 offset:1024
	ds_write_b16_d16_hi v3, v8 offset:5152
	ds_write_b16 v3, v9 offset:9280
	ds_write_b16_d16_hi v3, v9 offset:13408
	s_waitcnt vmcnt(10)
	v_cvt_pk_bf16_f32 v8, v120, v121
	v_cvt_pk_bf16_f32 v9, v122, v123
	ds_write_b16 v3, v8 offset:17536
	ds_write_b16_d16_hi v3, v8 offset:21664
	ds_write_b16 v3, v9 offset:25792
	ds_write_b16_d16_hi v3, v9 offset:29920
	s_waitcnt vmcnt(9)
	v_cvt_pk_bf16_f32 v8, v124, v125
	v_cvt_pk_bf16_f32 v9, v126, v127
	ds_write_b16 v3, v8 offset:34048
	ds_write_b16_d16_hi v3, v8 offset:38176
	ds_write_b16 v3, v9 offset:42304
	ds_write_b16_d16_hi v3, v9 offset:46432
	s_waitcnt vmcnt(8)
	v_cvt_pk_bf16_f32 v8, v128, v129
	v_cvt_pk_bf16_f32 v9, v130, v131
	ds_write_b16 v3, v8 offset:50560
	ds_write_b16_d16_hi v3, v8 offset:54688
	ds_write_b16 v3, v9 offset:58816
	ds_write_b16_d16_hi v3, v9 offset:62944
	s_waitcnt vmcnt(7)
	v_cvt_pk_bf16_f32 v8, v132, v133
	v_cvt_pk_bf16_f32 v9, v134, v135
	ds_write_b16 v3, v8 offset:2048
	ds_write_b16_d16_hi v3, v8 offset:6176
	ds_write_b16 v3, v9 offset:10304
	ds_write_b16_d16_hi v3, v9 offset:14432
	s_waitcnt vmcnt(6)
	v_cvt_pk_bf16_f32 v8, v136, v137
	v_cvt_pk_bf16_f32 v9, v138, v139
	ds_write_b16 v3, v8 offset:18560
	ds_write_b16_d16_hi v3, v8 offset:22688
	ds_write_b16 v3, v9 offset:26816
	ds_write_b16_d16_hi v3, v9 offset:30944
	s_waitcnt vmcnt(5)
	v_cvt_pk_bf16_f32 v8, v140, v141
	v_cvt_pk_bf16_f32 v9, v142, v143
	ds_write_b16 v3, v8 offset:35072
	ds_write_b16_d16_hi v3, v8 offset:39200
	ds_write_b16 v3, v9 offset:43328
	ds_write_b16_d16_hi v3, v9 offset:47456
	s_waitcnt vmcnt(4)
	v_cvt_pk_bf16_f32 v8, v148, v149
	v_cvt_pk_bf16_f32 v9, v150, v151
	ds_write_b16 v3, v8 offset:51584
	ds_write_b16_d16_hi v3, v8 offset:55712
	ds_write_b16 v3, v9 offset:59840
	ds_write_b16_d16_hi v3, v9 offset:63968
	s_waitcnt vmcnt(3)
	v_cvt_pk_bf16_f32 v8, v152, v153
	v_cvt_pk_bf16_f32 v9, v154, v155
	ds_write_b16 v3, v8 offset:3072
	ds_write_b16_d16_hi v3, v8 offset:7200
	ds_write_b16 v3, v9 offset:11328
	ds_write_b16_d16_hi v3, v9 offset:15456
	s_waitcnt vmcnt(2)
	v_cvt_pk_bf16_f32 v8, v156, v157
	v_cvt_pk_bf16_f32 v9, v158, v159
	ds_write_b16 v3, v8 offset:19584
	ds_write_b16_d16_hi v3, v8 offset:23712
	ds_write_b16 v3, v9 offset:27840
	ds_write_b16_d16_hi v3, v9 offset:31968
	s_waitcnt vmcnt(1)
	v_cvt_pk_bf16_f32 v8, v160, v161
	v_cvt_pk_bf16_f32 v9, v162, v163
	ds_write_b16 v3, v8 offset:36096
	ds_write_b16_d16_hi v3, v8 offset:40224
	ds_write_b16 v3, v9 offset:44352
	ds_write_b16_d16_hi v3, v9 offset:48480
	s_waitcnt vmcnt(0)
	v_cvt_pk_bf16_f32 v8, v164, v165
	v_cvt_pk_bf16_f32 v9, v166, v167
	ds_write_b16 v3, v8 offset:52608
	ds_write_b16_d16_hi v3, v8 offset:56736
	ds_write_b16 v3, v9 offset:60864
	ds_write_b16_d16_hi v3, v9 offset:64992
	s_or_b64 exec, exec, s[0:1]
	s_lshl_b32 s2, s94, 3
	s_add_i32 s6, s93, s2
	s_cmp_lt_i32 s6, 0x8400
	s_waitcnt lgkmcnt(0)
	s_barrier
; __device__ __forceinline__ void phase_ln_in(const Frame& F) {
;     ...
;     const float* MOD = (const float*)(F.ws + WS_MOD); float* GATES = (float*)(F.ws + WS_GATES); bf16_t* U = (bf16_t*)(F.ws + WS_U);
;     const int lane = F.lane, wid = F.wid, fr = lane & 15, fq = lane >> 4;
;     const float bias = (F.tid & 15) < 8 ? F.in[11][F.tid & 15] : F.in[12][(F.tid & 15) - 8];
;     for (int r = F.bid * 8 + wid; r < M; r += F.G * 8) {
	s_cbranch_scc0 .LBB0_155
	v_and_b32_e32 v3, 15, v192
	v_lshlrev_b32_e32 v32, 2, v3
	v_mov_b32_e32 v33, 0
	s_movk_i32 s0, 0xffe0
	v_lshl_add_u64 v[0:1], s[84:85], 0, v[32:33]
	s_mov_b32 s1, -1
	v_lshl_add_u64 v[0:1], v[0:1], 0, s[0:1]
	v_lshl_add_u64 v[4:5], s[82:83], 0, v[32:33]
	v_cmp_gt_u32_e32 vcc, 8, v3
	v_mul_u32_u24_e32 v6, 0x810, v3
	s_add_u32 s3, s66, 0x4000
	v_cndmask_b32_e32 v1, v1, v5, vcc
	v_cndmask_b32_e32 v0, v0, v4, vcc
	global_load_dword v38, v[0:1], off
	v_and_b32_e32 v3, 48, v147
	s_addc_u32 s26, s67, 0
	s_add_i32 s7, 0, 0x10200
	v_lshlrev_b32_e32 v1, 1, v6
	v_lshl_or_b32 v3, s93, 9, v3
	s_add_i32 s8, 0, 0x20400
	v_add3_u32 v40, 0, v1, v3
	v_add_u32_e32 v7, s8, v32
	v_add3_u32 v41, s7, v1, v3
	v_and_b32_e32 v1, 0x70, v192
	v_lshl_add_u32 v42, v1, 2, v7
	v_mbcnt_lo_u32_b32 v1, -1, 0
	v_mbcnt_hi_u32_b32 v1, -1, v1
	v_lshl_add_u32 v3, s93, 10, v7
	v_and_b32_e32 v7, 64, v1
	v_add_u32_e32 v7, 64, v7
	v_xor_b32_e32 v9, 32, v1
	v_cmp_lt_i32_e32 vcc, v9, v7
	v_lshl_add_u64 v[18:19], s[66:67], 0, v[32:33]
	s_mov_b64 s[12:13], 0x244000
	v_cndmask_b32_e32 v9, v1, v9, vcc
	v_lshlrev_b32_e32 v44, 2, v9
	v_xor_b32_e32 v9, 16, v1
	v_cmp_lt_i32_e32 vcc, v9, v7
	s_mul_i32 s0, s93, 0x1020
	v_lshl_add_u64 v[34:35], v[18:19], 0, s[12:13]
	v_cndmask_b32_e32 v9, v1, v9, vcc
	v_lshlrev_b32_e32 v45, 2, v9
	v_xor_b32_e32 v9, 8, v1
	v_cmp_lt_i32_e32 vcc, v9, v7
	v_readlane_b32 s12, v254, 36
	s_add_i32 s0, s7, s0
	v_cndmask_b32_e32 v9, v1, v9, vcc
	v_lshlrev_b32_e32 v46, 2, v9
	v_xor_b32_e32 v9, 4, v1
	v_cmp_lt_i32_e32 vcc, v9, v7
	v_lshlrev_b32_e32 v0, 3, v147
	s_lshl_b32 s10, s92, 3
	v_cndmask_b32_e32 v9, v1, v9, vcc
	v_lshlrev_b32_e32 v47, 2, v9
	v_xor_b32_e32 v9, 2, v1
	v_cmp_lt_i32_e32 vcc, v9, v7
	v_readlane_b32 s13, v254, 37
	s_ashr_i32 s7, s6, 31
	v_cndmask_b32_e32 v9, v1, v9, vcc
	v_lshlrev_b32_e32 v48, 2, v9
	v_xor_b32_e32 v9, 1, v1
	v_cmp_lt_i32_e32 vcc, v9, v7
	v_lshlrev_b32_e32 v2, 2, v147
	v_lshlrev_b32_e32 v4, 4, v147
	v_cndmask_b32_e32 v1, v1, v9, vcc
	v_lshlrev_b32_e32 v49, 2, v1
	v_mov_b32_e32 v1, v33
	v_lshl_add_u64 v[36:37], s[12:13], 0, v[0:1]
	s_ashr_i32 s11, s10, 31
	s_lshl_b64 s[12:13], s[6:7], 13
	v_add_u32_e32 v39, s0, v0
	s_movk_i32 s0, 0x80
	v_and_b32_e32 v5, 0x300, v4
	v_or_b32_e32 v4, 0x100, v2
	v_or_b32_e32 v6, 0x200, v2
	v_or_b32_e32 v8, 0x300, v2
	v_or_b32_e32 v10, 0x400, v2
	v_or_b32_e32 v12, 0x500, v2
	v_or_b32_e32 v14, 0x600, v2
	v_or_b32_e32 v16, 0x700, v2
	s_add_u32 s12, s44, s12
	s_mov_b32 s9, 0
	v_cmp_gt_u32_e64 s[0:1], s0, v192
	v_lshrrev_b32_e32 v43, 4, v192
	s_addc_u32 s13, s45, s13
	s_lshl_b64 s[14:15], s[10:11], 13
	v_lshlrev_b32_e32 v32, 2, v2
	s_movk_i32 s27, 0x1000
	v_mov_b32_e32 v50, 0x3727c5ac
	s_mov_b32 s28, 0x800000
	v_lshlrev_b32_e32 v51, 2, v4
	v_lshlrev_b32_e32 v52, 2, v6
	v_lshlrev_b32_e32 v53, 2, v8
	v_lshlrev_b32_e32 v54, 2, v10
	v_lshlrev_b32_e32 v55, 2, v12
	v_lshlrev_b32_e32 v56, 2, v14
	v_lshlrev_b32_e32 v57, 2, v16
	v_add_u32_e32 v58, v3, v5
	v_add_u32_e32 v199, 0x1000, v32
	s_mov_b32 s29, 0
	s_branch .LBB0_149

; __device__ __forceinline__ void phase_ln_in(const Frame& F) {
;     ...
;     for (int r = F.bid * 8 + wid; r < M; r += F.G * 8) {
;         const float* xr = r < MP ? F.in[0] + (size_t)r * D : F.in[1] + (size_t)(r - MP) * D; const int cd = cond_of_row(r);
;         f32x4 xv[8]; float s = 0.f;
; #pragma unroll
;         for (int j = 0; j < 8; ++j) { xv[j] = *(const f32x4*)(xr + j * 256 + lane * 4); s += (xv[j][0] + xv[j][1]) + (xv[j][2] + xv[j][3]); }
;         const float mu = wave_sum(s) * (1.0f / D); float q = 0.f;
; #pragma unroll
;         for (int j = 0; j < 8; ++j) { xv[j] = xv[j] - mu; q += (xv[j][0] * xv[j][0] + xv[j][1] * xv[j][1]) + (xv[j][2] * xv[j][2] + xv[j][3] * xv[j][3]); }
;         const float rstd = rsqrtf(wave_sum(q) * (1.0f / D) + LN_EPS);
;         const float* sh = MOD + (size_t)cd * MODW; const float* sc = sh + D;
.LBB0_153:
	s_cmp_lg_u32 s29, 0
	s_cbranch_scc1 .Lp1_have
	global_load_dwordx4 v[228:231], v32, s[22:23]
	global_load_dwordx4 v[224:227], v32, s[22:23] offset:1024
	global_load_dwordx4 v[220:223], v32, s[22:23] offset:2048
	global_load_dwordx4 v[216:219], v32, s[22:23] offset:3072
	global_load_dwordx4 v[212:215], v199, s[22:23]
	global_load_dwordx4 v[208:211], v199, s[22:23] offset:1024
	global_load_dwordx4 v[204:207], v199, s[22:23] offset:2048
	global_load_dwordx4 v[200:203], v199, s[22:23] offset:3072
	s_mov_b32 s29, 1
.Lp1_have:
	s_waitcnt vmcnt(0)
	v_mov_b64_e32 v[0:1], v[200:201]
	v_mov_b64_e32 v[2:3], v[202:203]
	v_mov_b64_e32 v[4:5], v[204:205]
	v_mov_b64_e32 v[6:7], v[206:207]
	v_mov_b64_e32 v[8:9], v[208:209]
	v_mov_b64_e32 v[10:11], v[210:211]
	v_mov_b64_e32 v[12:13], v[212:213]
	v_mov_b64_e32 v[14:15], v[214:215]
	v_mov_b64_e32 v[16:17], v[216:217]
	v_mov_b64_e32 v[18:19], v[218:219]
	v_mov_b64_e32 v[20:21], v[220:221]
	v_mov_b64_e32 v[22:23], v[222:223]
	v_mov_b64_e32 v[24:25], v[224:225]
	v_mov_b64_e32 v[26:27], v[226:227]
	v_mov_b64_e32 v[28:29], v[228:229]
	v_mov_b64_e32 v[30:31], v[230:231]
	s_lshr_b32 s8, s8, 5
	s_ashr_i32 s20, s20, 11
	s_add_i32 s8, s8, 16
	s_and_b64 s[18:19], s[18:19], exec
	s_cselect_b32 s8, s20, s8
	s_mul_hi_i32 s19, s8, 0xc000
	s_mul_i32 s8, s8, 0xc000
	s_add_u32 s18, s3, s8
	s_addc_u32 s19, s26, s19
	s_add_u32 s20, s18, 0x2000
	s_addc_u32 s21, s19, 0
	s_lshl_b64 s[16:17], s[16:17], 12
	global_load_dwordx4 v[100:103], v32, s[20:21]
	global_load_dwordx4 v[104:107], v32, s[18:19]
	global_load_dwordx4 v[108:111], v51, s[20:21]
	global_load_dwordx4 v[112:115], v32, s[18:19] offset:1024
	global_load_dwordx4 v[116:119], v52, s[20:21]
	global_load_dwordx4 v[120:123], v32, s[18:19] offset:2048
	global_load_dwordx4 v[124:127], v53, s[20:21]
	global_load_dwordx4 v[128:131], v32, s[18:19] offset:3072
	global_load_dwordx4 v[132:135], v54, s[20:21]
	global_load_dwordx4 v[136:139], v54, s[18:19]
	global_load_dwordx4 v[140:143], v55, s[20:21]
	global_load_dwordx4 v[148:151], v55, s[18:19]
	global_load_dwordx4 v[152:155], v56, s[20:21]
	global_load_dwordx4 v[156:159], v56, s[18:19]
	global_load_dwordx4 v[160:163], v57, s[20:21]
	global_load_dwordx4 v[164:167], v57, s[18:19]
	s_add_i32 s31, s93, s2
	s_add_i32 s31, s31, s10
	s_mov_b64 s[34:35], s[22:23]
	s_cmp_lt_i32 s31, 0x8000
	s_cbranch_scc0 .Lp1_ns
	s_add_u32 s34, s12, s14
	s_addc_u32 s35, s13, s15
	s_branch .Lp1_pdone
.Lp1_ns:
	s_cmp_lt_i32 s31, 0x8400
	s_cbranch_scc0 .Lp1_pdone
	s_add_i32 s31, s31, 0xffff8000
	s_lshl_b32 s31, s31, 13
	s_add_u32 s34, s46, s31
	s_addc_u32 s35, s47, 0
.Lp1_pdone:
	global_load_dwordx4 v[228:231], v32, s[34:35]
	global_load_dwordx4 v[224:227], v32, s[34:35] offset:1024
	global_load_dwordx4 v[220:223], v32, s[34:35] offset:2048
	global_load_dwordx4 v[216:219], v32, s[34:35] offset:3072
	global_load_dwordx4 v[212:215], v199, s[34:35]
	global_load_dwordx4 v[208:211], v199, s[34:35] offset:1024
	global_load_dwordx4 v[204:207], v199, s[34:35] offset:2048
	global_load_dwordx4 v[200:203], v199, s[34:35] offset:3072
	v_mov_b32_e32 v60, v28
	v_mov_b32_e32 v61, v24
	v_mov_b32_e32 v62, v29
	v_mov_b32_e32 v63, v25
	v_mov_b32_e32 v64, v30
	v_mov_b32_e32 v65, v26
	v_mov_b32_e32 v66, v31
	v_mov_b32_e32 v67, v27
	v_mov_b32_e32 v68, v21
	v_mov_b32_e32 v69, v22
	v_mov_b32_e32 v70, v20
	v_mov_b32_e32 v71, v23
	v_pk_add_f32 v[60:61], v[60:61], v[62:63]
	v_pk_add_f32 v[62:63], v[64:65], v[66:67]
	v_pk_add_f32 v[64:65], v[68:69], v[70:71]
	v_pk_add_f32 v[60:61], v[60:61], v[62:63]
	v_pk_add_f32 v[62:63], v[64:65], v[64:65] op_sel:[0,1] op_sel_hi:[1,0]
	v_add_f32_e32 v59, 0, v60
	v_add_f32_e32 v72, v16, v17
	v_add_f32_e32 v74, v18, v19
	v_mov_b32_e32 v65, v12
	v_mov_b32_e32 v73, v14
	v_mov_b32_e32 v75, v15
	v_mov_b32_e32 v63, v13
	v_add_f32_e32 v64, v59, v61
	v_mov_b32_e32 v66, v9
	v_mov_b32_e32 v67, v10
	v_mov_b32_e32 v68, v8
	v_mov_b32_e32 v69, v11
	v_pk_add_f32 v[72:73], v[72:73], v[74:75]
	v_pk_add_f32 v[62:63], v[64:65], v[62:63]
	v_pk_add_f32 v[66:67], v[66:67], v[68:69]
	v_pk_add_f32 v[62:63], v[62:63], v[72:73]
	v_pk_add_f32 v[60:61], v[66:67], v[66:67] op_sel:[0,1] op_sel_hi:[1,0]
	v_pk_add_f32 v[62:63], v[62:63], v[62:63] op_sel:[0,1] op_sel_hi:[1,0]
	v_add_f32_e32 v70, v4, v5
	v_add_f32_e32 v76, v6, v7
	v_mov_b32_e32 v71, v2
	v_mov_b32_e32 v77, v3
	v_mov_b32_e32 v61, v1
	v_mov_b32_e32 v63, v0
	v_pk_add_f32 v[68:69], v[70:71], v[76:77]
	v_pk_add_f32 v[60:61], v[62:63], v[60:61]
	s_nop 0
	v_pk_add_f32 v[60:61], v[60:61], v[68:69]
	s_nop 0
	v_add_f32_e32 v59, v60, v61
	ds_bpermute_b32 v60, v44, v59
	s_waitcnt lgkmcnt(0)
	v_add_f32_e32 v59, v59, v60
	ds_bpermute_b32 v60, v45, v59
	s_waitcnt lgkmcnt(0)
	v_add_f32_e32 v59, v59, v60
	ds_bpermute_b32 v60, v46, v59
	s_waitcnt lgkmcnt(0)
	v_add_f32_e32 v59, v59, v60
	ds_bpermute_b32 v60, v47, v59
	s_waitcnt lgkmcnt(0)
	v_add_f32_e32 v59, v59, v60
	ds_bpermute_b32 v60, v48, v59
	s_waitcnt lgkmcnt(0)
	v_add_f32_e32 v59, v59, v60
	ds_bpermute_b32 v68, v49, v59
	s_waitcnt lgkmcnt(0)
; #define LAS __attribute__((address_space(3)))
; __device__ __forceinline__ unsigned cvt_pk_bf16(float lo, float hi) { unsigned r; asm volatile("v_cvt_pk_bf16_f32 %0, %1, %2" : "=v"(r) : "v"(lo), "v"(hi)); return r; }
; __device__ __forceinline__ void phase_ln_in(const Frame& F) {
;     ...
;         const float mu = wave_sum(s) * (1.0f / D); float q = 0.f;
; #pragma unroll
;         for (int j = 0; j < 8; ++j) { xv[j] = xv[j] - mu; q += (xv[j][0] * xv[j][0] + xv[j][1] * xv[j][1]) + (xv[j][2] * xv[j][2] + xv[j][3] * xv[j][3]); }
;         const float rstd = rsqrtf(wave_sum(q) * (1.0f / D) + LN_EPS);
;         const float* sh = MOD + (size_t)cd * MODW; const float* sc = sh + D;
; #pragma unroll
;         for (int j = 0; j < 8; ++j) { const int e = j * 256 + lane * 4; const f32x4 scv = *(const f32x4*)(sc + e), shv = *(const f32x4*)(sh + e);
;             const f32x4 u = xv[j] * rstd * (scv + 1.0f) + shv;
;             u32x2 w; w.x = cvt_pk_bf16(u[0], u[1]); w.y = cvt_pk_bf16(u[2], u[3]); *(u32x2*)(U + (size_t)r * D + e) = w; *(LAS u32x2*)(ub + wid * LP + e) = w; }
	v_add_f32_e32 v59, v59, v68
	v_fmamk_f32 v31, v59, 0xba000000, v31
	v_fmamk_f32 v29, v59, 0xba000000, v29
	v_fmamk_f32 v27, v59, 0xba000000, v27
	v_fmamk_f32 v25, v59, 0xba000000, v25
	v_fmamk_f32 v30, v59, 0xba000000, v30
	v_fmac_f32_e32 v28, 0xba000000, v59
	v_fmamk_f32 v26, v59, 0xba000000, v26
	v_fmac_f32_e32 v24, 0xba000000, v59
	v_fmamk_f32 v21, v59, 0xba000000, v21
	v_fmamk_f32 v20, v59, 0xba000000, v20
	v_fmamk_f32 v23, v59, 0xba000000, v23
	v_fmac_f32_e32 v22, 0xba000000, v59
	v_fmamk_f32 v69, v59, 0xba000000, v17
	v_fmamk_f32 v68, v59, 0xba000000, v16
	v_mov_b32_e32 v16, v29
	v_mov_b32_e32 v17, v25
	v_mov_b32_e32 v74, v31
	v_mov_b32_e32 v75, v27
	v_fmamk_f32 v71, v59, 0xba000000, v15
	v_fmamk_f32 v70, v59, 0xba000000, v14
	v_mov_b32_e32 v14, v28
	v_mov_b32_e32 v15, v24
	v_mov_b32_e32 v72, v30
	v_mov_b32_e32 v73, v26
	v_pk_mul_f32 v[76:77], v[22:23], v[22:23]
	v_pk_mul_f32 v[78:79], v[20:21], v[20:21]
	v_pk_mul_f32 v[16:17], v[16:17], v[16:17]
	v_pk_mul_f32 v[74:75], v[74:75], v[74:75]
	v_fmac_f32_e32 v18, 0xba000000, v59
	v_pk_mov_b32 v[84:85], v[78:79], v[76:77] op_sel:[1,0]
	v_mov_b32_e32 v79, v77
	v_pk_fma_f32 v[14:15], v[14:15], v[14:15], v[16:17]
	v_pk_fma_f32 v[16:17], v[72:73], v[72:73], v[74:75]
	v_fmamk_f32 v19, v59, 0xba000000, v19
	v_mul_f32_e32 v80, v68, v68
	v_mul_f32_e32 v82, v18, v18
	v_pk_add_f32 v[72:73], v[84:85], v[78:79]
	v_pk_add_f32 v[14:15], v[14:15], v[16:17]
	v_fmamk_f32 v13, v59, 0xba000000, v13
	v_fmac_f32_e32 v12, 0xba000000, v59
	v_pk_fma_f32 v[76:77], v[68:69], v[68:69], v[80:81] op_sel_hi:[1,1,0]
	v_pk_fma_f32 v[80:81], v[18:19], v[18:19], v[82:83] op_sel_hi:[1,1,0]
	v_pk_add_f32 v[16:17], v[72:73], v[72:73] op_sel_hi:[0,1]
	v_pk_add_f32 v[14:15], v[14:15], v[14:15] op_sel_hi:[0,1]
	v_mul_f32_e32 v76, v12, v12
	v_mul_f32_e32 v80, v13, v13
	v_mul_f32_e32 v16, v70, v70
	v_mul_f32_e32 v14, v71, v71
	v_fmamk_f32 v9, v59, 0xba000000, v9
	v_fmamk_f32 v8, v59, 0xba000000, v8
	v_fmamk_f32 v11, v59, 0xba000000, v11
	v_pk_add_f32 v[72:73], v[76:77], v[80:81]
	v_pk_add_f32 v[14:15], v[16:17], v[14:15]
	v_fmac_f32_e32 v10, 0xba000000, v59
	v_pk_add_f32 v[14:15], v[72:73], v[14:15]
	v_pk_mul_f32 v[16:17], v[10:11], v[10:11]
	v_pk_mul_f32 v[72:73], v[8:9], v[8:9]
	v_fmac_f32_e32 v6, 0xba000000, v59
	v_pk_mov_b32 v[74:75], v[72:73], v[16:17] op_sel:[1,0]
	v_mov_b32_e32 v73, v17
	v_pk_add_f32 v[16:17], v[74:75], v[72:73]
	v_fmamk_f32 v72, v59, 0xba000000, v4
	v_fmamk_f32 v73, v59, 0xba000000, v5
	v_mul_f32_e32 v4, v72, v72
	v_pk_fma_f32 v[4:5], v[72:73], v[72:73], v[4:5] op_sel_hi:[1,1,0]
	v_fmamk_f32 v7, v59, 0xba000000, v7
	v_mul_f32_e32 v4, v6, v6
	v_pk_add_f32 v[14:15], v[14:15], v[14:15] op_sel_hi:[0,1]
	v_pk_add_f32 v[16:17], v[16:17], v[16:17] op_sel_hi:[0,1]
	v_pk_fma_f32 v[74:75], v[6:7], v[6:7], v[4:5] op_sel_hi:[1,1,0]
	v_fmamk_f32 v77, v59, 0xba000000, v3
	v_fmamk_f32 v76, v59, 0xba000000, v2
	v_fmamk_f32 v1, v59, 0xba000000, v1
	v_fmac_f32_e32 v0, 0xba000000, v59
	v_mul_f32_e32 v4, v0, v0
	v_mul_f32_e32 v74, v1, v1
	v_mul_f32_e32 v16, v76, v76
	v_mul_f32_e32 v14, v77, v77
	v_pk_add_f32 v[2:3], v[4:5], v[74:75]
	v_pk_add_f32 v[4:5], v[16:17], v[14:15]
	s_waitcnt vmcnt(22)
	v_mov_b64_e32 v[60:61], v[100:101]
	v_mov_b64_e32 v[62:63], v[102:103]
	v_mov_b64_e32 v[64:65], v[104:105]
	v_mov_b64_e32 v[66:67], v[106:107]
	v_pk_add_f32 v[16:17], v[60:61], 1.0 op_sel_hi:[1,0]
	v_pk_add_f32 v[2:3], v[2:3], v[4:5]
	s_nop 0
	v_add_f32_e32 v2, v2, v3
	ds_bpermute_b32 v3, v44, v2
	s_waitcnt lgkmcnt(0)
	v_add_f32_e32 v2, v2, v3
	ds_bpermute_b32 v3, v45, v2
	s_waitcnt lgkmcnt(0)
	v_add_f32_e32 v2, v2, v3
	ds_bpermute_b32 v3, v46, v2
	s_waitcnt lgkmcnt(0)
	v_add_f32_e32 v2, v2, v3
	ds_bpermute_b32 v3, v47, v2
	s_waitcnt lgkmcnt(0)
	v_add_f32_e32 v2, v2, v3
	ds_bpermute_b32 v3, v48, v2
	s_waitcnt lgkmcnt(0)
	v_add_f32_e32 v2, v2, v3
	ds_bpermute_b32 v3, v49, v2
	s_waitcnt lgkmcnt(0)
	v_add_f32_e32 v2, v2, v3
	v_fmamk_f32 v2, v2, 0x3a000000, v50
	v_mul_f32_e32 v3, 0x4b800000, v2
	v_cmp_gt_f32_e32 vcc, s28, v2
	s_nop 1
	v_cndmask_b32_e32 v2, v2, v3, vcc
	v_rsq_f32_e32 v4, v2
	v_pk_add_f32 v[2:3], v[62:63], 1.0 op_sel_hi:[1,0]
	v_mul_f32_e32 v5, 0x45800000, v4
	v_cndmask_b32_e32 v62, v4, v5, vcc
	v_pk_mul_f32 v[4:5], v[28:29], v[62:63] op_sel_hi:[1,0]
	v_pk_mul_f32 v[14:15], v[30:31], v[62:63] op_sel_hi:[1,0]
	v_lshl_add_u64 v[30:31], v[36:37], 0, s[16:17]
	v_pk_fma_f32 v[2:3], v[2:3], v[14:15], v[66:67]
	v_pk_fma_f32 v[4:5], v[16:17], v[4:5], v[64:65]
	v_pk_mul_f32 v[24:25], v[24:25], v[62:63] op_sel_hi:[1,0]
	v_cvt_pk_bf16_f32 v28, v4, v5
	v_cvt_pk_bf16_f32 v29, v2, v3
	global_store_dwordx2 v[30:31], v[28:29], off
	v_pk_mul_f32 v[26:27], v[26:27], v[62:63] op_sel_hi:[1,0]
	ds_write_b64 v39, v[28:29]
	v_pk_mul_f32 v[20:21], v[20:21], v[62:63] op_sel_hi:[1,0]
	v_pk_mul_f32 v[22:23], v[22:23], v[62:63] op_sel_hi:[1,0]
	v_pk_mul_f32 v[18:19], v[18:19], v[62:63] op_sel_hi:[1,0]
	v_pk_mul_f32 v[12:13], v[12:13], v[62:63] op_sel_hi:[1,0]
	v_pk_mul_f32 v[8:9], v[8:9], v[62:63] op_sel_hi:[1,0]
	v_pk_mul_f32 v[10:11], v[10:11], v[62:63] op_sel_hi:[1,0]
	v_pk_mul_f32 v[6:7], v[6:7], v[62:63] op_sel_hi:[1,0]
	v_pk_mul_f32 v[0:1], v[0:1], v[62:63] op_sel_hi:[1,0]
	s_waitcnt vmcnt(21)
	v_mov_b64_e32 v[2:3], v[108:109]
	v_mov_b64_e32 v[4:5], v[110:111]
	v_mov_b64_e32 v[14:15], v[112:113]
	v_mov_b64_e32 v[16:17], v[114:115]
	v_pk_add_f32 v[4:5], v[4:5], 1.0 op_sel_hi:[1,0]
	v_pk_add_f32 v[2:3], v[2:3], 1.0 op_sel_hi:[1,0]
	v_pk_fma_f32 v[4:5], v[4:5], v[26:27], v[16:17]
	v_pk_fma_f32 v[2:3], v[2:3], v[24:25], v[14:15]
	s_nop 0
	v_cvt_pk_bf16_f32 v24, v2, v3
	v_cvt_pk_bf16_f32 v25, v4, v5
	global_store_dwordx2 v[30:31], v[24:25], off offset:512
	ds_write_b64 v39, v[24:25] offset:512
	s_waitcnt vmcnt(20)
; #define LAS __attribute__((address_space(3)))
; __device__ __forceinline__ unsigned cvt_pk_bf16(float lo, float hi) { unsigned r; asm volatile("v_cvt_pk_bf16_f32 %0, %1, %2" : "=v"(r) : "v"(lo), "v"(hi)); return r; }
; __device__ __forceinline__ f32x4 mfma16(bf16x8 a, bf16x8 b, f32x4 c) { return __builtin_amdgcn_mfma_f32_16x16x32_bf16(a, b, c, 0, 0, 0); }
; __device__ __forceinline__ void phase_ln_in(const Frame& F) {
;     ...
; #pragma unroll
;         for (int j = 0; j < 8; ++j) { const int e = j * 256 + lane * 4; const f32x4 scv = *(const f32x4*)(sc + e), shv = *(const f32x4*)(sh + e);
;             const f32x4 u = xv[j] * rstd * (scv + 1.0f) + shv;
;             u32x2 w; w.x = cvt_pk_bf16(u[0], u[1]); w.y = cvt_pk_bf16(u[2], u[3]); *(u32x2*)(U + (size_t)r * D + e) = w; *(LAS u32x2*)(ub + wid * LP + e) = w; }
;         __syncthreads();
;         f32x4 acc = (f32x4){0.f, 0.f, 0.f, 0.f};
; #pragma unroll
;         for (int kk = 0; kk < 8; ++kk) { const int k0 = 256 * wid + 32 * kk + 8 * fq;
;             const bf16x8 af = *(const LAS bf16x8*)(ub + fr * LP + k0), bfv = *(const LAS bf16x8*)(wgB + fr * LP + k0); acc = mfma16(af, bfv, acc); }
; #pragma unroll
;         for (int i = 0; i < 4; ++i) red[(wid * 16 + 4 * fq + i) * 16 + fr] = acc[i];
;         __syncthreads();
;         if (F.tid < 128) { const int m = F.tid >> 4, n = F.tid & 15; float t = bias;
; #pragma unroll
;             for (int w = 0; w < 8; ++w) t += red[(w * 16 + m) * 16 + n];
;             GATES[(size_t)(r - wid + m) * 16 + n] = t; }
	v_mov_b64_e32 v[2:3], v[116:117]
	v_mov_b64_e32 v[4:5], v[118:119]
	v_mov_b64_e32 v[14:15], v[120:121]
	v_mov_b64_e32 v[16:17], v[122:123]
	v_pk_add_f32 v[4:5], v[4:5], 1.0 op_sel_hi:[1,0]
	v_pk_add_f32 v[2:3], v[2:3], 1.0 op_sel_hi:[1,0]
	v_pk_fma_f32 v[4:5], v[4:5], v[22:23], v[16:17]
	v_pk_fma_f32 v[2:3], v[2:3], v[20:21], v[14:15]
	v_pk_mul_f32 v[22:23], v[68:69], v[62:63] op_sel_hi:[1,0]
	v_cvt_pk_bf16_f32 v20, v2, v3
	v_cvt_pk_bf16_f32 v21, v4, v5
	global_store_dwordx2 v[30:31], v[20:21], off offset:1024
	ds_write_b64 v39, v[20:21] offset:1024
	v_pk_mul_f32 v[20:21], v[70:71], v[62:63] op_sel_hi:[1,0]
	s_waitcnt vmcnt(19)
	v_mov_b64_e32 v[2:3], v[124:125]
	v_mov_b64_e32 v[4:5], v[126:127]
	v_mov_b64_e32 v[14:15], v[128:129]
	v_mov_b64_e32 v[16:17], v[130:131]
	v_pk_add_f32 v[4:5], v[4:5], 1.0 op_sel_hi:[1,0]
	v_pk_add_f32 v[2:3], v[2:3], 1.0 op_sel_hi:[1,0]
	v_pk_fma_f32 v[4:5], v[4:5], v[18:19], v[16:17]
	v_pk_fma_f32 v[2:3], v[2:3], v[22:23], v[14:15]
	s_nop 0
	v_cvt_pk_bf16_f32 v18, v2, v3
	v_cvt_pk_bf16_f32 v19, v4, v5
	global_store_dwordx2 v[30:31], v[18:19], off offset:1536
	ds_write_b64 v39, v[18:19] offset:1536
	s_waitcnt vmcnt(18)
	v_mov_b64_e32 v[2:3], v[132:133]
	v_mov_b64_e32 v[4:5], v[134:135]
	v_mov_b64_e32 v[14:15], v[136:137]
	v_mov_b64_e32 v[16:17], v[138:139]
	v_pk_add_f32 v[4:5], v[4:5], 1.0 op_sel_hi:[1,0]
	v_pk_add_f32 v[2:3], v[2:3], 1.0 op_sel_hi:[1,0]
	v_pk_fma_f32 v[4:5], v[4:5], v[20:21], v[16:17]
	v_pk_fma_f32 v[2:3], v[2:3], v[12:13], v[14:15]
	s_nop 0
	v_cvt_pk_bf16_f32 v16, v2, v3
	v_cvt_pk_bf16_f32 v17, v4, v5
	global_store_dwordx2 v[30:31], v[16:17], off offset:2048
	ds_write_b64 v39, v[16:17] offset:2048
	s_waitcnt vmcnt(17)
	v_mov_b64_e32 v[2:3], v[140:141]
	v_mov_b64_e32 v[4:5], v[142:143]
	v_mov_b64_e32 v[12:13], v[148:149]
	v_mov_b64_e32 v[14:15], v[150:151]
	v_pk_add_f32 v[4:5], v[4:5], 1.0 op_sel_hi:[1,0]
	v_pk_add_f32 v[2:3], v[2:3], 1.0 op_sel_hi:[1,0]
	v_pk_fma_f32 v[4:5], v[10:11], v[4:5], v[14:15]
	v_pk_fma_f32 v[2:3], v[8:9], v[2:3], v[12:13]
	v_pk_mul_f32 v[14:15], v[72:73], v[62:63] op_sel_hi:[1,0]
	v_cvt_pk_bf16_f32 v12, v2, v3
	v_cvt_pk_bf16_f32 v13, v4, v5
	global_store_dwordx2 v[30:31], v[12:13], off offset:2560
	ds_write_b64 v39, v[12:13] offset:2560
	v_pk_mul_f32 v[12:13], v[76:77], v[62:63] op_sel_hi:[1,0]
	s_waitcnt vmcnt(16)
	v_mov_b64_e32 v[2:3], v[152:153]
	v_mov_b64_e32 v[4:5], v[154:155]
	v_mov_b64_e32 v[8:9], v[156:157]
	v_mov_b64_e32 v[10:11], v[158:159]
	v_pk_add_f32 v[4:5], v[4:5], 1.0 op_sel_hi:[1,0]
	v_pk_add_f32 v[2:3], v[2:3], 1.0 op_sel_hi:[1,0]
	v_pk_fma_f32 v[4:5], v[6:7], v[4:5], v[10:11]
	v_pk_fma_f32 v[2:3], v[14:15], v[2:3], v[8:9]
	s_nop 0
	v_cvt_pk_bf16_f32 v10, v2, v3
	v_cvt_pk_bf16_f32 v11, v4, v5
	global_store_dwordx2 v[30:31], v[10:11], off offset:3072
	ds_write_b64 v39, v[10:11] offset:3072
	s_waitcnt vmcnt(15)
	v_mov_b64_e32 v[2:3], v[160:161]
	v_mov_b64_e32 v[4:5], v[162:163]
	v_mov_b64_e32 v[6:7], v[164:165]
	v_mov_b64_e32 v[8:9], v[166:167]
	v_pk_add_f32 v[2:3], v[2:3], 1.0 op_sel_hi:[1,0]
	v_pk_add_f32 v[4:5], v[4:5], 1.0 op_sel_hi:[1,0]
	v_pk_fma_f32 v[0:1], v[0:1], v[2:3], v[6:7]
	v_pk_fma_f32 v[4:5], v[12:13], v[4:5], v[8:9]
	v_cvt_pk_bf16_f32 v0, v0, v1
	s_nop 0
	v_cvt_pk_bf16_f32 v1, v4, v5
	global_store_dwordx2 v[30:31], v[0:1], off offset:3584
	ds_write_b64 v39, v[0:1] offset:3584
	s_waitcnt lgkmcnt(0)
	s_barrier
	ds_read_b128 v[0:3], v41
	ds_read_b128 v[4:7], v41 offset:64
	ds_read_b128 v[8:11], v40
	ds_read_b128 v[12:15], v40 offset:64
	s_waitcnt lgkmcnt(1)
	v_mfma_f32_16x16x32_bf16 v[0:3], v[0:3], v[8:11], 0
	ds_read_b128 v[8:11], v41 offset:128
	ds_read_b128 v[16:19], v41 offset:192
	s_waitcnt lgkmcnt(2)
	v_mfma_f32_16x16x32_bf16 v[0:3], v[4:7], v[12:15], v[0:3]
	ds_read_b128 v[4:7], v40 offset:128
	ds_read_b128 v[12:15], v40 offset:192
	s_waitcnt lgkmcnt(1)
	v_mfma_f32_16x16x32_bf16 v[0:3], v[8:11], v[4:7], v[0:3]
	ds_read_b128 v[4:7], v41 offset:256
	ds_read_b128 v[8:11], v41 offset:320
	s_waitcnt lgkmcnt(2)
	v_mfma_f32_16x16x32_bf16 v[0:3], v[16:19], v[12:15], v[0:3]
	ds_read_b128 v[12:15], v40 offset:256
	ds_read_b128 v[16:19], v40 offset:320
	s_waitcnt lgkmcnt(1)
	v_mfma_f32_16x16x32_bf16 v[0:3], v[4:7], v[12:15], v[0:3]
	ds_read_b128 v[4:7], v41 offset:384
	ds_read_b128 v[12:15], v41 offset:448
	s_waitcnt lgkmcnt(2)
	v_mfma_f32_16x16x32_bf16 v[0:3], v[8:11], v[16:19], v[0:3]
	ds_read_b128 v[8:11], v40 offset:384
	ds_read_b128 v[16:19], v40 offset:448
	s_waitcnt lgkmcnt(1)
	v_mfma_f32_16x16x32_bf16 v[0:3], v[4:7], v[8:11], v[0:3]
	s_waitcnt lgkmcnt(0)
	v_mfma_f32_16x16x32_bf16 v[0:3], v[12:15], v[16:19], v[0:3]
	s_nop 7
	ds_write2_b32 v58, v0, v1 offset1:16
	ds_write2_b32 v58, v2, v3 offset0:32 offset1:48
	s_waitcnt lgkmcnt(0)
	s_barrier
	s_and_saveexec_b64 s[16:17], s[0:1]
	s_cbranch_execz .LBB0_148
	ds_read2st64_b32 v[0:1], v42 offset1:4
	ds_read2st64_b32 v[2:3], v42 offset0:8 offset1:12
	ds_read2st64_b32 v[4:5], v42 offset0:16 offset1:20
	ds_read2st64_b32 v[6:7], v42 offset0:24 offset1:28
	v_add_u32_e32 v8, s2, v43
	s_waitcnt lgkmcnt(3)
	v_add_f32_e32 v0, v38, v0
	v_add_f32_e32 v0, v0, v1
	s_waitcnt lgkmcnt(2)
	v_add_f32_e32 v0, v0, v2
	v_add_f32_e32 v0, v0, v3
	s_waitcnt lgkmcnt(1)
	v_add_f32_e32 v0, v0, v4
	v_add_f32_e32 v0, v0, v5
	s_waitcnt lgkmcnt(0)
	v_add_f32_e32 v0, v0, v6
	v_ashrrev_i32_e32 v9, 31, v8
	v_add_f32_e32 v2, v0, v7
	v_lshlrev_b64 v[0:1], 6, v[8:9]
	v_lshl_add_u64 v[0:1], v[34:35], 0, v[0:1]
	global_store_dword v[0:1], v2, off
	s_branch .LBB0_148
